# gate/up GEMM K-loop: rebalance LDS-DMA staging between the two super-phases (A half-tile [b][0] staged one super-phase later: 4+4 loads instead of 2+6; waits re-derived vmcnt 8/6)
# baseline (speedup 1.0000x reference)
; #define PG8_STAGE(bufoff, gbase, voff) do { _Pragma("unroll") for (int _i = 0; _i < 2; ++_i) \
;         __builtin_amdgcn_global_load_lds((const unsigned*)((const char*)(gbase) + (voff)[_i]), (PG8_LAS unsigned*)(lds + (bufoff) + ldsw + _i * 8192), 16, 0, 0); } while (0)
; #define PG8_LDA(dst, b, h) do { _Pragma("unroll") for (int m = 0; m < 4; ++m) _Pragma("unroll") for (int k = 0; k < 2; ++k) dst[m][k] = *(const PG8_LAS bf16x8*)(lds + PG8_SA(b, h) + aoff + m * 2048 + k * 1024); } while (0)
; #define PG8_LDB(dst, b, h) do { _Pragma("unroll") for (int n = 0; n < 2; ++n) _Pragma("unroll") for (int k = 0; k < 2; ++k) dst[n][k] = *(const PG8_LAS bf16x8*)(lds + PG8_SB(b, h) + boff + n * 2048 + k * 1024); } while (0)
; #define PG8_MMA(ai, bj, At, Bt) do { __builtin_amdgcn_s_setprio(1); _Pragma("unroll") for (int m = 0; m < 4; ++m) _Pragma("unroll") for (int n = 0; n < 2; ++n) _Pragma("unroll") for (int k = 0; k < 2; ++k) \
;         acc[ai][bj][m][n] = __builtin_amdgcn_mfma_f32_16x16x32_bf16(Bt[n][k], At[m][k], acc[ai][bj][m][n], 0, 0, 0); __builtin_amdgcn_s_setprio(0); } while (0)
; #define PG8_WAIT_V(n) asm volatile("s_waitcnt vmcnt(" #n ")" ::: "memory")
; #define PG8_WAIT_L(n) asm volatile("s_waitcnt lgkmcnt(" #n ")" ::: "memory")
; #define PG8_BAR __builtin_amdgcn_s_barrier()
; #define PG8_SCHED __builtin_amdgcn_sched_barrier(0)
; template <class Epi, class Sched, bool ALIGN_EPI = false, bool SP2 = false>
; __device__ __forceinline__ void gemm_phase(PG8_LAS unsigned char* lds, const Gemm g, const Sched& S, const Epi& E) {
;     ...
;             PG8_LDB(B0, 0, 0); PG8_LDB(B1, 0, 1); PG8_SCHED; PG8_LDA(At, 0, 0); PG8_STAGE(PG8_SA(1, 1), a1 + hstep, voffA);
;             PG8_WAIT_V(8); PG8_WAIT_L(0); PG8_BAR; PG8_MMA(0, 0, At, B0); PG8_MMA(0, 1, At, B1); PG8_BAR; PG8_SCHED;
;             PG8_LDA(At, 0, 1); PG8_STAGE(PG8_SB(0, 0), b2, voffB); PG8_STAGE(PG8_SB(0, 1), b2 + hstep, voffB); PG8_STAGE(PG8_SA(0, 0), a2, voffA);
;             PG8_WAIT_V(8); PG8_WAIT_L(0); PG8_BAR; PG8_MMA(1, 0, At, B0); PG8_MMA(1, 1, At, B1); PG8_BAR; PG8_SCHED;
.LBB0_431:
	s_add_u32 s54, s42, s52
	s_addc_u32 s55, s43, s53
	s_add_u32 s54, s54, 0x100
	s_addc_u32 s55, s55, 0
	s_add_u32 s75, s29, s52
	s_addc_u32 s76, s33, s53
	s_cmpk_eq_i32 s52, 0xf00
	s_cselect_b32 s57, s25, s55
	s_cselect_b32 s56, s47, s54
	s_cselect_b32 s55, s45, s76
	s_cselect_b32 s54, s73, s75
	s_add_u32 s76, s42, s52
	s_addc_u32 s77, s43, s53
	s_add_u32 s76, s76, 0x80
	s_addc_u32 s77, s77, 0
	s_add_i32 s75, 0, 0x10000
	v_add_u32_e32 v152, s75, v145
	s_add_i32 s78, 0, 0x14000
	ds_read_b128 v[148:151], v152
	ds_read_b128 v[170:173], v152 offset:1024
	ds_read_b128 v[174:177], v152 offset:2048
	ds_read_b128 v[178:181], v152 offset:3072
	v_add_u32_e32 v152, s78, v145
	ds_read_b128 v[182:185], v152
	ds_read_b128 v[186:189], v152 offset:1024
	ds_read_b128 v[190:193], v152 offset:2048
	ds_read_b128 v[194:197], v152 offset:3072
	v_lshl_add_u64 v[214:215], v[140:141], 0, s[52:53]
	v_lshl_add_u64 v[236:237], s[76:77], 0, v[128:129]
	v_lshl_add_u64 v[238:239], s[76:77], 0, v[132:133]
	s_mov_b32 m0, s70
	ds_read_b128 v[198:201], v147
	ds_read_b128 v[202:205], v147 offset:1024
	ds_read_b128 v[206:209], v147 offset:2048
	ds_read_b128 v[210:213], v147 offset:3072
	ds_read_b128 v[220:223], v147 offset:4096
	ds_read_b128 v[224:227], v147 offset:5120
	ds_read_b128 v[228:231], v147 offset:6144
	ds_read_b128 v[232:235], v147 offset:7168
	global_load_lds_dwordx4 v[236:237], off
	s_mov_b32 m0, s71
	s_nop 0
	global_load_lds_dwordx4 v[238:239], off
	s_add_i32 m0, s15, 0xc000
	s_nop 0
	global_load_lds_dwordx4 v[214:215], off
	v_lshl_add_u64 v[214:215], v[142:143], 0, s[52:53]
	s_add_i32 m0, s15, 0xe000
	s_nop 0
	global_load_lds_dwordx4 v[214:215], off
	s_waitcnt vmcnt(8)
	s_waitcnt lgkmcnt(0)
	s_barrier
	s_setprio 1
	s_waitcnt lgkmcnt(0)
	v_mfma_f32_16x16x32_bf16 v[124:127], v[148:151], v[198:201], v[124:127]
	v_mfma_f32_16x16x32_bf16 v[120:123], v[174:177], v[198:201], v[120:123]
	v_mfma_f32_16x16x32_bf16 v[116:119], v[148:151], v[206:209], v[116:119]
	v_mfma_f32_16x16x32_bf16 v[112:115], v[174:177], v[206:209], v[112:115]
	v_mfma_f32_16x16x32_bf16 v[108:111], v[148:151], v[220:223], v[108:111]
	v_mfma_f32_16x16x32_bf16 v[104:107], v[174:177], v[220:223], v[104:107]
	v_mfma_f32_16x16x32_bf16 v[100:103], v[148:151], v[228:231], v[100:103]
	v_mfma_f32_16x16x32_bf16 v[96:99], v[174:177], v[228:231], v[96:99]
	v_mfma_f32_16x16x32_bf16 v[124:127], v[170:173], v[202:205], v[124:127]
	v_mfma_f32_16x16x32_bf16 v[120:123], v[178:181], v[202:205], v[120:123]
	v_mfma_f32_16x16x32_bf16 v[116:119], v[170:173], v[210:213], v[116:119]
	v_mfma_f32_16x16x32_bf16 v[112:115], v[178:181], v[210:213], v[112:115]
	v_mfma_f32_16x16x32_bf16 v[108:111], v[170:173], v[224:227], v[108:111]
	v_mfma_f32_16x16x32_bf16 v[104:107], v[178:181], v[224:227], v[104:107]
	v_mfma_f32_16x16x32_bf16 v[100:103], v[170:173], v[232:235], v[100:103]
	v_mfma_f32_16x16x32_bf16 v[96:99], v[178:181], v[232:235], v[96:99]
	s_setprio 0
	s_setprio 1
	v_mfma_f32_16x16x32_bf16 v[92:95], v[182:185], v[198:201], v[92:95]
	v_mfma_f32_16x16x32_bf16 v[88:91], v[190:193], v[198:201], v[88:91]
	v_mfma_f32_16x16x32_bf16 v[84:87], v[182:185], v[206:209], v[84:87]
	v_mfma_f32_16x16x32_bf16 v[80:83], v[190:193], v[206:209], v[80:83]
	v_mfma_f32_16x16x32_bf16 v[76:79], v[182:185], v[220:223], v[76:79]
	v_mfma_f32_16x16x32_bf16 v[72:75], v[190:193], v[220:223], v[72:75]
	v_mfma_f32_16x16x32_bf16 v[68:71], v[182:185], v[228:231], v[68:71]
	v_mfma_f32_16x16x32_bf16 v[64:67], v[190:193], v[228:231], v[64:67]
	v_mfma_f32_16x16x32_bf16 v[92:95], v[186:189], v[202:205], v[92:95]
	v_mfma_f32_16x16x32_bf16 v[88:91], v[194:197], v[202:205], v[88:91]
	v_mfma_f32_16x16x32_bf16 v[84:87], v[186:189], v[210:213], v[84:87]
	v_mfma_f32_16x16x32_bf16 v[80:83], v[194:197], v[210:213], v[80:83]
	v_mfma_f32_16x16x32_bf16 v[76:79], v[186:189], v[224:227], v[76:79]
	v_mfma_f32_16x16x32_bf16 v[72:75], v[194:197], v[224:227], v[72:75]
	v_mfma_f32_16x16x32_bf16 v[68:71], v[186:189], v[232:235], v[68:71]
	v_mfma_f32_16x16x32_bf16 v[64:67], v[194:197], v[232:235], v[64:67]
	s_setprio 0
	s_barrier
	s_add_i32 s75, s75, s65
	v_lshl_add_u64 v[214:215], s[54:55], 0, v[130:131]
	s_mov_b32 m0, s75
	ds_read_b128 v[198:201], v147 offset:16384
	ds_read_b128 v[202:205], v147 offset:17408
	ds_read_b128 v[206:209], v147 offset:18432
	ds_read_b128 v[210:213], v147 offset:19456
	ds_read_b128 v[220:223], v147 offset:20480
	ds_read_b128 v[224:227], v147 offset:21504
	ds_read_b128 v[228:231], v147 offset:22528
	ds_read_b128 v[232:235], v147 offset:23552
	global_load_lds_dwordx4 v[214:215], off
	s_add_i32 m0, s75, 0x2000
	s_add_u32 s76, s54, 0x80000
	v_lshl_add_u64 v[236:237], s[54:55], 0, v[134:135]
	s_addc_u32 s77, s55, 0
	s_add_i32 s75, s78, s65
	global_load_lds_dwordx4 v[236:237], off
	v_lshl_add_u64 v[238:239], s[76:77], 0, v[130:131]
	s_mov_b32 m0, s75
	s_nop 0
	global_load_lds_dwordx4 v[238:239], off
	v_lshl_add_u64 v[238:239], s[76:77], 0, v[134:135]
	s_add_i32 m0, s75, 0x2000
	s_nop 0
	global_load_lds_dwordx4 v[238:239], off
	s_waitcnt vmcnt(6)
	s_waitcnt lgkmcnt(0)
	s_barrier
; #define PG8_STAGE(bufoff, gbase, voff) do { _Pragma("unroll") for (int _i = 0; _i < 2; ++_i) \
;         __builtin_amdgcn_global_load_lds((const unsigned*)((const char*)(gbase) + (voff)[_i]), (PG8_LAS unsigned*)(lds + (bufoff) + ldsw + _i * 8192), 16, 0, 0); } while (0)
; #define PG8_LDA(dst, b, h) do { _Pragma("unroll") for (int m = 0; m < 4; ++m) _Pragma("unroll") for (int k = 0; k < 2; ++k) dst[m][k] = *(const PG8_LAS bf16x8*)(lds + PG8_SA(b, h) + aoff + m * 2048 + k * 1024); } while (0)
; #define PG8_LDB(dst, b, h) do { _Pragma("unroll") for (int n = 0; n < 2; ++n) _Pragma("unroll") for (int k = 0; k < 2; ++k) dst[n][k] = *(const PG8_LAS bf16x8*)(lds + PG8_SB(b, h) + boff + n * 2048 + k * 1024); } while (0)
; #define PG8_MMA(ai, bj, At, Bt) do { __builtin_amdgcn_s_setprio(1); _Pragma("unroll") for (int m = 0; m < 4; ++m) _Pragma("unroll") for (int n = 0; n < 2; ++n) _Pragma("unroll") for (int k = 0; k < 2; ++k) \
;         acc[ai][bj][m][n] = __builtin_amdgcn_mfma_f32_16x16x32_bf16(Bt[n][k], At[m][k], acc[ai][bj][m][n], 0, 0, 0); __builtin_amdgcn_s_setprio(0); } while (0)
; #define PG8_WAIT_V(n) asm volatile("s_waitcnt vmcnt(" #n ")" ::: "memory")
; #define PG8_WAIT_L(n) asm volatile("s_waitcnt lgkmcnt(" #n ")" ::: "memory")
; #define PG8_BAR __builtin_amdgcn_s_barrier()
; #define PG8_SCHED __builtin_amdgcn_sched_barrier(0)
; template <class Epi, class Sched, bool ALIGN_EPI = false, bool SP2 = false>
; __device__ __forceinline__ void gemm_phase(PG8_LAS unsigned char* lds, const Gemm g, const Sched& S, const Epi& E) {
;     ...
;             PG8_WAIT_V(8); PG8_WAIT_L(0); PG8_BAR; PG8_MMA(1, 0, At, B0); PG8_MMA(1, 1, At, B1); PG8_BAR; PG8_SCHED;
;             PG8_LDB(B0, 1, 0); PG8_LDB(B1, 1, 1); PG8_SCHED; PG8_LDA(At, 1, 0); PG8_STAGE(PG8_SA(0, 1), a2 + hstep, voffA);
;             PG8_WAIT_V(8); PG8_WAIT_L(0); PG8_BAR; PG8_MMA(0, 0, At, B0); PG8_MMA(0, 1, At, B1); PG8_BAR; PG8_SCHED;
	s_setprio 1
	s_waitcnt lgkmcnt(0)
	v_mfma_f32_16x16x32_bf16 v[60:63], v[148:151], v[198:201], v[60:63]
	v_mfma_f32_16x16x32_bf16 v[56:59], v[174:177], v[198:201], v[56:59]
	v_mfma_f32_16x16x32_bf16 v[52:55], v[148:151], v[206:209], v[52:55]
	v_mfma_f32_16x16x32_bf16 v[48:51], v[174:177], v[206:209], v[48:51]
	v_mfma_f32_16x16x32_bf16 v[44:47], v[148:151], v[220:223], v[44:47]
	v_mfma_f32_16x16x32_bf16 v[40:43], v[174:177], v[220:223], v[40:43]
	v_mfma_f32_16x16x32_bf16 v[36:39], v[148:151], v[228:231], v[36:39]
	v_mfma_f32_16x16x32_bf16 v[32:35], v[174:177], v[228:231], v[32:35]
	v_mfma_f32_16x16x32_bf16 v[60:63], v[170:173], v[202:205], v[60:63]
	v_mfma_f32_16x16x32_bf16 v[56:59], v[178:181], v[202:205], v[56:59]
	v_mfma_f32_16x16x32_bf16 v[52:55], v[170:173], v[210:213], v[52:55]
	v_mfma_f32_16x16x32_bf16 v[48:51], v[178:181], v[210:213], v[48:51]
	v_mfma_f32_16x16x32_bf16 v[44:47], v[170:173], v[224:227], v[44:47]
	v_mfma_f32_16x16x32_bf16 v[40:43], v[178:181], v[224:227], v[40:43]
	v_mfma_f32_16x16x32_bf16 v[36:39], v[170:173], v[232:235], v[36:39]
	v_mfma_f32_16x16x32_bf16 v[32:35], v[178:181], v[232:235], v[32:35]
	s_setprio 0
	s_setprio 1
	v_mfma_f32_16x16x32_bf16 v[28:31], v[182:185], v[198:201], v[28:31]
	v_mfma_f32_16x16x32_bf16 v[24:27], v[190:193], v[198:201], v[24:27]
	v_mfma_f32_16x16x32_bf16 v[20:23], v[182:185], v[206:209], v[20:23]
	v_mfma_f32_16x16x32_bf16 v[16:19], v[190:193], v[206:209], v[16:19]
	v_mfma_f32_16x16x32_bf16 v[12:15], v[182:185], v[220:223], v[12:15]
	v_mfma_f32_16x16x32_bf16 v[8:11], v[190:193], v[220:223], v[8:11]
	v_mfma_f32_16x16x32_bf16 v[4:7], v[182:185], v[228:231], v[4:7]
	v_mfma_f32_16x16x32_bf16 v[0:3], v[190:193], v[228:231], v[0:3]
	v_mfma_f32_16x16x32_bf16 v[28:31], v[186:189], v[202:205], v[28:31]
	v_mfma_f32_16x16x32_bf16 v[24:27], v[194:197], v[202:205], v[24:27]
	v_mfma_f32_16x16x32_bf16 v[20:23], v[186:189], v[210:213], v[20:23]
	v_mfma_f32_16x16x32_bf16 v[16:19], v[194:197], v[210:213], v[16:19]
	v_mfma_f32_16x16x32_bf16 v[12:15], v[186:189], v[224:227], v[12:15]
	v_mfma_f32_16x16x32_bf16 v[8:11], v[194:197], v[224:227], v[8:11]
	v_mfma_f32_16x16x32_bf16 v[4:7], v[186:189], v[232:235], v[4:7]
	v_mfma_f32_16x16x32_bf16 v[0:3], v[194:197], v[232:235], v[0:3]
	s_setprio 0
	s_barrier
	s_add_i32 s75, 0, 0x18000
	v_add_u32_e32 v152, s75, v145
	s_add_i32 s76, 0, 0x1c000
	ds_read_b128 v[148:151], v152
	ds_read_b128 v[170:173], v152 offset:1024
	ds_read_b128 v[174:177], v152 offset:2048
	ds_read_b128 v[178:181], v152 offset:3072
	v_add_u32_e32 v152, s76, v145
	ds_read_b128 v[182:185], v152
	ds_read_b128 v[186:189], v152 offset:1024
	ds_read_b128 v[190:193], v152 offset:2048
	ds_read_b128 v[194:197], v152 offset:3072
	v_lshl_add_u64 v[238:239], s[56:57], 0, v[128:129]
	v_lshl_add_u64 v[240:241], s[56:57], 0, v[132:133]
	s_add_u32 s56, s56, 0x80000
	s_addc_u32 s57, s57, 0
	s_mov_b32 m0, s15
	v_lshl_add_u64 v[242:243], s[56:57], 0, v[128:129]
	ds_read_b128 v[198:201], v147 offset:32768
	ds_read_b128 v[202:205], v147 offset:33792
	ds_read_b128 v[206:209], v147 offset:34816
	ds_read_b128 v[210:213], v147 offset:35840
	ds_read_b128 v[220:223], v147 offset:36864
	ds_read_b128 v[224:227], v147 offset:37888
	ds_read_b128 v[228:231], v147 offset:38912
	ds_read_b128 v[232:235], v147 offset:39936
	global_load_lds_dwordx4 v[238:239], off
	s_mov_b32 m0, s17
	s_nop 0
	global_load_lds_dwordx4 v[240:241], off
	s_mov_b32 m0, s68
	s_nop 0
	global_load_lds_dwordx4 v[242:243], off
	v_lshl_add_u64 v[242:243], s[56:57], 0, v[132:133]
	s_mov_b32 m0, s69
	s_nop 0
	global_load_lds_dwordx4 v[242:243], off
	s_waitcnt vmcnt(8)
	s_waitcnt lgkmcnt(0)
	s_barrier
; #define PG8_STAGE(bufoff, gbase, voff) do { _Pragma("unroll") for (int _i = 0; _i < 2; ++_i) \
;         __builtin_amdgcn_global_load_lds((const unsigned*)((const char*)(gbase) + (voff)[_i]), (PG8_LAS unsigned*)(lds + (bufoff) + ldsw + _i * 8192), 16, 0, 0); } while (0)
; #define PG8_LDA(dst, b, h) do { _Pragma("unroll") for (int m = 0; m < 4; ++m) _Pragma("unroll") for (int k = 0; k < 2; ++k) dst[m][k] = *(const PG8_LAS bf16x8*)(lds + PG8_SA(b, h) + aoff + m * 2048 + k * 1024); } while (0)
; #define PG8_MMA(ai, bj, At, Bt) do { __builtin_amdgcn_s_setprio(1); _Pragma("unroll") for (int m = 0; m < 4; ++m) _Pragma("unroll") for (int n = 0; n < 2; ++n) _Pragma("unroll") for (int k = 0; k < 2; ++k) \
;         acc[ai][bj][m][n] = __builtin_amdgcn_mfma_f32_16x16x32_bf16(Bt[n][k], At[m][k], acc[ai][bj][m][n], 0, 0, 0); __builtin_amdgcn_s_setprio(0); } while (0)
; #define PG8_WAIT_V(n) asm volatile("s_waitcnt vmcnt(" #n ")" ::: "memory")
; #define PG8_WAIT_L(n) asm volatile("s_waitcnt lgkmcnt(" #n ")" ::: "memory")
; #define PG8_BAR __builtin_amdgcn_s_barrier()
; #define PG8_SCHED __builtin_amdgcn_sched_barrier(0)
; template <class Epi, class Sched, bool ALIGN_EPI = false, bool SP2 = false>
; __device__ __forceinline__ void gemm_phase(PG8_LAS unsigned char* lds, const Gemm g, const Sched& S, const Epi& E) {
;     ...
;         for (int t = 0; t < nt; t += 2) {
;             const bool last = (t == nt - 2);
;             const char* a1 = cA + (size_t)(t + 1) * kstep;
;             const char* a2 = last ? nA : cA + (size_t)(t + 2) * kstep; const char* b2 = last ? nB : cB + (size_t)(t + 2) * kstep;
;     ...
;             PG8_WAIT_V(8); PG8_WAIT_L(0); PG8_BAR; PG8_MMA(0, 0, At, B0); PG8_MMA(0, 1, At, B1); PG8_BAR; PG8_SCHED;
;             PG8_LDA(At, 1, 1); PG8_STAGE(PG8_SB(1, 0), b3, voffB); PG8_STAGE(PG8_SB(1, 1), b3 + hstep, voffB); PG8_STAGE(PG8_SA(1, 0), a3, voffA);
;             PG8_WAIT_V(8); PG8_WAIT_L(0); PG8_BAR; PG8_MMA(1, 0, At, B0); PG8_MMA(1, 1, At, B1); PG8_BAR; PG8_SCHED;
	s_setprio 1
	s_waitcnt lgkmcnt(0)
	v_mfma_f32_16x16x32_bf16 v[124:127], v[148:151], v[198:201], v[124:127]
	v_mfma_f32_16x16x32_bf16 v[120:123], v[174:177], v[198:201], v[120:123]
	v_mfma_f32_16x16x32_bf16 v[116:119], v[148:151], v[206:209], v[116:119]
	v_mfma_f32_16x16x32_bf16 v[112:115], v[174:177], v[206:209], v[112:115]
	v_mfma_f32_16x16x32_bf16 v[108:111], v[148:151], v[220:223], v[108:111]
	v_mfma_f32_16x16x32_bf16 v[104:107], v[174:177], v[220:223], v[104:107]
	v_mfma_f32_16x16x32_bf16 v[100:103], v[148:151], v[228:231], v[100:103]
	v_mfma_f32_16x16x32_bf16 v[96:99], v[174:177], v[228:231], v[96:99]
	v_mfma_f32_16x16x32_bf16 v[124:127], v[170:173], v[202:205], v[124:127]
	v_mfma_f32_16x16x32_bf16 v[120:123], v[178:181], v[202:205], v[120:123]
	v_mfma_f32_16x16x32_bf16 v[116:119], v[170:173], v[210:213], v[116:119]
	v_mfma_f32_16x16x32_bf16 v[112:115], v[178:181], v[210:213], v[112:115]
	v_mfma_f32_16x16x32_bf16 v[108:111], v[170:173], v[224:227], v[108:111]
	v_mfma_f32_16x16x32_bf16 v[104:107], v[178:181], v[224:227], v[104:107]
	v_mfma_f32_16x16x32_bf16 v[100:103], v[170:173], v[232:235], v[100:103]
	v_mfma_f32_16x16x32_bf16 v[96:99], v[178:181], v[232:235], v[96:99]
	s_setprio 0
	s_setprio 1
	v_mfma_f32_16x16x32_bf16 v[92:95], v[182:185], v[198:201], v[92:95]
	v_mfma_f32_16x16x32_bf16 v[88:91], v[190:193], v[198:201], v[88:91]
	v_mfma_f32_16x16x32_bf16 v[84:87], v[182:185], v[206:209], v[84:87]
	v_mfma_f32_16x16x32_bf16 v[80:83], v[190:193], v[206:209], v[80:83]
	v_mfma_f32_16x16x32_bf16 v[76:79], v[182:185], v[220:223], v[76:79]
	v_mfma_f32_16x16x32_bf16 v[72:75], v[190:193], v[220:223], v[72:75]
	v_mfma_f32_16x16x32_bf16 v[68:71], v[182:185], v[228:231], v[68:71]
	v_mfma_f32_16x16x32_bf16 v[64:67], v[190:193], v[228:231], v[64:67]
	v_mfma_f32_16x16x32_bf16 v[92:95], v[186:189], v[202:205], v[92:95]
	v_mfma_f32_16x16x32_bf16 v[88:91], v[194:197], v[202:205], v[88:91]
	v_mfma_f32_16x16x32_bf16 v[84:87], v[186:189], v[210:213], v[84:87]
	v_mfma_f32_16x16x32_bf16 v[80:83], v[194:197], v[210:213], v[80:83]
	v_mfma_f32_16x16x32_bf16 v[76:79], v[186:189], v[224:227], v[76:79]
	v_mfma_f32_16x16x32_bf16 v[72:75], v[194:197], v[224:227], v[72:75]
	v_mfma_f32_16x16x32_bf16 v[68:71], v[186:189], v[232:235], v[68:71]
	v_mfma_f32_16x16x32_bf16 v[64:67], v[194:197], v[232:235], v[64:67]
	s_setprio 0
	s_barrier
	s_add_i32 s56, s75, s65
	v_lshl_add_u64 v[214:215], v[214:215], 0, s[90:91]
	s_mov_b32 m0, s56
	ds_read_b128 v[198:201], v147 offset:49152
	ds_read_b128 v[202:205], v147 offset:50176
	ds_read_b128 v[206:209], v147 offset:51200
	ds_read_b128 v[210:213], v147 offset:52224
	ds_read_b128 v[220:223], v147 offset:53248
	ds_read_b128 v[224:227], v147 offset:54272
	ds_read_b128 v[228:231], v147 offset:55296
	ds_read_b128 v[232:235], v147 offset:56320
	global_load_lds_dwordx4 v[214:215], off
	s_add_i32 m0, s56, 0x2000
	s_add_u32 s54, s54, 0x80080
	v_lshl_add_u64 v[214:215], v[236:237], 0, s[90:91]
	s_addc_u32 s55, s55, 0
	s_add_i32 s56, s76, s65
	global_load_lds_dwordx4 v[214:215], off
	v_lshl_add_u64 v[214:215], s[54:55], 0, v[130:131]
	s_mov_b32 m0, s56
	s_nop 0
	global_load_lds_dwordx4 v[214:215], off
	v_lshl_add_u64 v[214:215], s[54:55], 0, v[134:135]
	s_add_i32 m0, s56, 0x2000
	s_nop 0
	global_load_lds_dwordx4 v[214:215], off
	s_waitcnt vmcnt(6)
	s_waitcnt lgkmcnt(0)
	s_barrier
	s_setprio 1
	s_waitcnt lgkmcnt(0)
	v_mfma_f32_16x16x32_bf16 v[60:63], v[148:151], v[198:201], v[60:63]
	v_mfma_f32_16x16x32_bf16 v[56:59], v[174:177], v[198:201], v[56:59]
	v_mfma_f32_16x16x32_bf16 v[52:55], v[148:151], v[206:209], v[52:55]
	v_mfma_f32_16x16x32_bf16 v[48:51], v[174:177], v[206:209], v[48:51]
	v_mfma_f32_16x16x32_bf16 v[44:47], v[148:151], v[220:223], v[44:47]
	v_mfma_f32_16x16x32_bf16 v[40:43], v[174:177], v[220:223], v[40:43]
	v_mfma_f32_16x16x32_bf16 v[36:39], v[148:151], v[228:231], v[36:39]
	v_mfma_f32_16x16x32_bf16 v[32:35], v[174:177], v[228:231], v[32:35]
	v_mfma_f32_16x16x32_bf16 v[60:63], v[170:173], v[202:205], v[60:63]
	v_mfma_f32_16x16x32_bf16 v[56:59], v[178:181], v[202:205], v[56:59]
	v_mfma_f32_16x16x32_bf16 v[52:55], v[170:173], v[210:213], v[52:55]
	v_mfma_f32_16x16x32_bf16 v[48:51], v[178:181], v[210:213], v[48:51]
	v_mfma_f32_16x16x32_bf16 v[44:47], v[170:173], v[224:227], v[44:47]
	v_mfma_f32_16x16x32_bf16 v[40:43], v[178:181], v[224:227], v[40:43]
	v_mfma_f32_16x16x32_bf16 v[36:39], v[170:173], v[232:235], v[36:39]
	v_mfma_f32_16x16x32_bf16 v[32:35], v[178:181], v[232:235], v[32:35]
	s_setprio 0
	s_setprio 1
	v_mfma_f32_16x16x32_bf16 v[28:31], v[182:185], v[198:201], v[28:31]
	v_mfma_f32_16x16x32_bf16 v[24:27], v[190:193], v[198:201], v[24:27]
	v_mfma_f32_16x16x32_bf16 v[20:23], v[182:185], v[206:209], v[20:23]
	v_mfma_f32_16x16x32_bf16 v[16:19], v[190:193], v[206:209], v[16:19]
	v_mfma_f32_16x16x32_bf16 v[12:15], v[182:185], v[220:223], v[12:15]
	v_mfma_f32_16x16x32_bf16 v[8:11], v[190:193], v[220:223], v[8:11]
	v_mfma_f32_16x16x32_bf16 v[4:7], v[182:185], v[228:231], v[4:7]
	v_mfma_f32_16x16x32_bf16 v[0:3], v[190:193], v[228:231], v[0:3]
	v_mfma_f32_16x16x32_bf16 v[28:31], v[186:189], v[202:205], v[28:31]
	v_mfma_f32_16x16x32_bf16 v[24:27], v[194:197], v[202:205], v[24:27]
	v_mfma_f32_16x16x32_bf16 v[20:23], v[186:189], v[210:213], v[20:23]
	v_mfma_f32_16x16x32_bf16 v[16:19], v[194:197], v[210:213], v[16:19]
	v_mfma_f32_16x16x32_bf16 v[12:15], v[186:189], v[224:227], v[12:15]
	v_mfma_f32_16x16x32_bf16 v[8:11], v[194:197], v[224:227], v[8:11]
	v_mfma_f32_16x16x32_bf16 v[4:7], v[186:189], v[232:235], v[4:7]
	v_mfma_f32_16x16x32_bf16 v[0:3], v[194:197], v[232:235], v[0:3]
	s_setprio 0
	s_barrier
	s_add_i32 s74, s74, 2
	s_add_u32 s52, s52, 0x100
	s_addc_u32 s53, s53, 0
	s_cmp_gt_u32 s74, 29
	s_cbranch_scc0 .LBB0_431
	s_and_b64 vcc, exec, s[26:27]
	s_cbranch_vccz .LBB0_434
	s_barrier
